# grid barrier: cache invalidate issued at arrival (leader: right after its L2 writeback) instead of after the release; unused per-XCC release add dropped
# speedup vs baseline: 1.0035x; 1.0032x over previous
.LBB0_2174:
	s_or_b64 exec, exec, s[26:27]
	v_cvt_f32_u32_e32 v5, v3
	s_waitcnt vmcnt(0)
	v_readfirstlane_b32 s2, v4
	v_sub_u32_e32 v4, 0, v3
	v_rcp_iflag_f32_e32 v5, v5
	v_add_u32_e32 v6, s2, v0
	v_mul_f32_e32 v5, 0x4f7ffffe, v5
	v_cvt_u32_f32_e32 v5, v5
	v_mul_lo_u32 v0, v4, v5
	v_mul_hi_u32 v0, v5, v0
	v_add_u32_e32 v0, v5, v0
	v_mul_hi_u32 v0, v6, v0
	v_mul_lo_u32 v4, v0, v3
	v_sub_u32_e32 v4, v6, v4
	v_add_u32_e32 v5, 1, v0
	v_cmp_ge_u32_e32 vcc, v4, v3
	s_nop 1
	v_cndmask_b32_e32 v0, v0, v5, vcc
	v_sub_u32_e32 v5, v4, v3
	v_cndmask_b32_e32 v4, v4, v5, vcc
	v_add_u32_e32 v5, 1, v0
	v_cmp_ge_u32_e32 vcc, v4, v3
	v_add_u32_e32 v4, 1, v6
	s_nop 0
	v_cndmask_b32_e32 v0, v0, v5, vcc
	v_mul_lo_u32 v5, v3, v0
	v_add_u32_e32 v3, v5, v3
	v_cmp_ne_u32_e32 vcc, v4, v3
	s_and_saveexec_b64 s[2:3], vcc
	s_xor_b64 s[26:27], exec, s[2:3]
	s_cbranch_execz .LBB0_2188
	v_readlane_b32 s2, v253, 32
	v_readlane_b32 s3, v253, 33
	s_waitcnt lgkmcnt(0)
	s_nop 3
	buffer_inv sc1
	global_load_dword v2, v1, s[2:3] sc1
	s_waitcnt vmcnt(0)
	v_cmp_eq_u32_e32 vcc, v2, v0
	s_and_saveexec_b64 s[30:31], vcc
	s_cbranch_execz .LBB0_2187
	s_mov_b32 s33, 1
	s_mov_b64 s[34:35], 0
	s_branch .LBB0_2178

.LBB0_2187:
	s_or_b64 exec, exec, s[30:31]
	s_waitcnt vmcnt(0)
	s_waitcnt vmcnt(0)

.LBB0_2189:
	s_mov_b64 s[26:27], exec
	buffer_wbl2 sc1
	s_waitcnt lgkmcnt(0)
	s_waitcnt vmcnt(0)
	buffer_inv sc1
	v_mbcnt_lo_u32_b32 v0, s26, 0
	v_mbcnt_hi_u32_b32 v0, s27, v0
	v_cmp_eq_u32_e32 vcc, 0, v0
	s_and_saveexec_b64 s[30:31], vcc
	s_cbranch_execz .LBB0_2191
	s_bcnt1_i32_b64 s2, s[26:27]
	v_mov_b32_e32 v3, s2
	v_readlane_b32 s2, v253, 30
	v_readlane_b32 s3, v253, 31
	s_nop 4
	global_atomic_add v3, v1, v3, s[2:3] sc0

.LBB0_2207:
	s_or_b64 exec, exec, s[26:27]
	s_mov_b64 s[26:27], exec
	v_mbcnt_lo_u32_b32 v0, s26, 0
	v_mbcnt_hi_u32_b32 v0, s27, v0
	v_cmp_eq_u32_e32 vcc, 0, v0
	s_waitcnt vmcnt(0)
	s_and_saveexec_b64 s[30:31], vcc
	s_cbranch_execnz .LBB0_2208
	s_getpc_b64 s[98:99]

.LBB0_2208:
	s_bcnt1_i32_b64 s2, s[26:27]
	v_mov_b32_e32 v0, s2
	v_readlane_b32 s2, v253, 28
	v_readlane_b32 s3, v253, 29
	s_nop 4
	s_getpc_b64 s[98:99]
